# P9 split-K fix-up: late partial loads and residual-row loads issued with the first batch (34 loads at once), stacked on v85
# speedup vs baseline: 1.0051x; 1.0023x over previous
.LBB0_2145:
	s_or_b64 exec, exec, s[60:61]
	v_mov_b32_e32 v130, v0
	v_readlane_b32 s36, v254, 62
	s_barrier
	s_lshr_b32 s17, s73, 2
	s_and_b32 vcc_lo, s73, 3
	v_readlane_b32 s37, v254, 63
	v_ashrrev_i32_e32 v131, 31, v130
	s_lshl_b32 s33, s17, 4
	v_lshl_add_u64 v[130:131], v[130:131], 4, s[36:37]
	s_lshl_b32 s36, vcc_lo, 1
	s_or_b32 s36, s33, s36
	s_ashr_i32 s59, s58, 31
	s_or_b32 s40, s36, 8
	s_lshl_b64 s[62:63], s[58:59], 17
	s_mov_b32 s37, s41
	s_lshl_b64 s[60:61], s[40:41], 12
	v_lshl_add_u64 v[132:133], v[130:131], 0, s[62:63]
	s_lshl_b64 s[62:63], s[36:37], 12
	s_or_b32 s40, s36, 1
	v_lshl_add_u64 v[134:135], v[132:133], 0, s[62:63]
	s_add_u32 s64, s62, 8
	s_addc_u32 s65, s63, 0
	s_or_b32 s40, s36, 9
	s_or_b32 s36, s58, 1
	global_load_dwordx2 v[154:155], v[134:135], off sc1
	v_lshl_add_u64 v[134:135], v[132:133], 0, s[64:65]
	s_add_u32 s66, s60, 8
	s_addc_u32 s67, s61, 0
	s_ashr_i32 s37, s36, 31
	global_load_dwordx2 v[156:157], v[134:135], off sc1
	v_lshl_add_u64 v[134:135], v[132:133], 0, s[60:61]
	v_lshl_add_u64 v[132:133], v[132:133], 0, s[66:67]
	s_lshl_b64 s[36:37], s[36:37], 17
	global_load_dwordx2 v[158:159], v[134:135], off sc1
	global_load_dwordx2 v[160:161], v[132:133], off sc1
	v_lshl_add_u64 v[132:133], v[130:131], 0, s[36:37]
	v_lshl_add_u64 v[134:135], v[132:133], 0, s[62:63]
	s_or_b32 s36, s58, 2
	global_load_dwordx2 v[162:163], v[134:135], off sc1
	v_lshl_add_u64 v[134:135], v[132:133], 0, s[64:65]
	s_ashr_i32 s37, s36, 31
	global_load_dwordx2 v[164:165], v[134:135], off sc1
	v_lshl_add_u64 v[134:135], v[132:133], 0, s[60:61]
	v_lshl_add_u64 v[132:133], v[132:133], 0, s[66:67]
	s_lshl_b64 s[36:37], s[36:37], 17
	global_load_dwordx2 v[166:167], v[134:135], off sc1
	global_load_dwordx2 v[168:169], v[132:133], off sc1
	v_lshl_add_u64 v[132:133], v[130:131], 0, s[36:37]
	v_lshl_add_u64 v[134:135], v[132:133], 0, s[62:63]
	s_or_b32 s36, s58, 3
	global_load_dwordx2 v[170:171], v[134:135], off sc1
	v_lshl_add_u64 v[134:135], v[132:133], 0, s[64:65]
	s_ashr_i32 s37, s36, 31
	global_load_dwordx2 v[172:173], v[134:135], off sc1
	v_lshl_add_u64 v[134:135], v[132:133], 0, s[60:61]
	v_lshl_add_u64 v[132:133], v[132:133], 0, s[66:67]
	s_lshl_b64 s[36:37], s[36:37], 17
	global_load_dwordx2 v[174:175], v[134:135], off sc1
	global_load_dwordx2 v[176:177], v[132:133], off sc1
	v_lshl_add_u64 v[132:133], v[130:131], 0, s[36:37]
	v_lshl_add_u64 v[134:135], v[132:133], 0, s[62:63]
	s_or_b32 s36, s58, 4
	global_load_dwordx2 v[178:179], v[134:135], off sc1
	v_lshl_add_u64 v[134:135], v[132:133], 0, s[64:65]
	s_ashr_i32 s37, s36, 31
	global_load_dwordx2 v[180:181], v[134:135], off sc1
	v_lshl_add_u64 v[134:135], v[132:133], 0, s[60:61]
	v_lshl_add_u64 v[132:133], v[132:133], 0, s[66:67]
	s_lshl_b64 s[36:37], s[36:37], 17
	global_load_dwordx2 v[182:183], v[134:135], off sc1
	global_load_dwordx2 v[184:185], v[132:133], off sc1
	v_lshl_add_u64 v[132:133], v[130:131], 0, s[36:37]
	v_lshl_add_u64 v[134:135], v[132:133], 0, s[62:63]
	global_load_dwordx2 v[186:187], v[134:135], off sc1
	v_lshl_add_u64 v[134:135], v[132:133], 0, s[64:65]
	global_load_dwordx2 v[188:189], v[134:135], off sc1
	v_lshl_add_u64 v[134:135], v[132:133], 0, s[60:61]
	global_load_dwordx2 v[190:191], v[134:135], off sc1
	v_lshl_add_u64 v[132:133], v[132:133], 0, s[66:67]
	global_load_dwordx2 v[192:193], v[132:133], off sc1
	s_or_b32 s36, s58, 5
	s_ashr_i32 s37, s36, 31
	s_lshl_b64 s[36:37], s[36:37], 17
	v_lshl_add_u64 v[132:133], v[130:131], 0, s[36:37]
	v_lshl_add_u64 v[134:135], v[132:133], 0, s[62:63]
	global_load_dwordx2 v[152:153], v[134:135], off sc1
	v_lshl_add_u64 v[134:135], v[132:133], 0, s[64:65]
	global_load_dwordx2 v[150:151], v[134:135], off sc1
	v_lshl_add_u64 v[134:135], v[132:133], 0, s[60:61]
	global_load_dwordx2 v[148:149], v[134:135], off sc1
	s_or_b32 s36, s58, 6
	s_ashr_i32 s37, s36, 31
	v_lshl_add_u64 v[132:133], v[132:133], 0, s[66:67]
	s_lshl_b64 s[36:37], s[36:37], 17
	global_load_dwordx2 v[144:145], v[132:133], off sc1
	v_lshl_add_u64 v[132:133], v[130:131], 0, s[36:37]
	v_lshl_add_u64 v[134:135], v[132:133], 0, s[62:63]
	s_or_b32 s36, s58, 7
	global_load_dwordx2 v[146:147], v[134:135], off sc1
	v_lshl_add_u64 v[134:135], v[132:133], 0, s[64:65]
	s_ashr_i32 s37, s36, 31
	global_load_dwordx2 v[142:143], v[134:135], off sc1
	v_lshl_add_u64 v[134:135], v[132:133], 0, s[60:61]
	s_lshl_b64 s[36:37], s[36:37], 17
	global_load_dwordx2 v[140:141], v[134:135], off sc1
	v_lshl_add_u64 v[132:133], v[132:133], 0, s[66:67]
	v_lshl_add_u64 v[130:131], v[130:131], 0, s[36:37]
	global_load_dwordx2 v[136:137], v[132:133], off sc1
	v_lshl_add_u64 v[132:133], v[130:131], 0, s[62:63]
	global_load_dwordx2 v[138:139], v[132:133], off sc1
	v_lshl_add_u64 v[132:133], v[130:131], 0, s[64:65]
	global_load_dwordx2 v[134:135], v[132:133], off sc1
	v_lshl_add_u64 v[2:3], v[130:131], 0, s[60:61]
	global_load_dwordx2 v[6:7], v[2:3], off sc1
	v_lshl_add_u64 v[4:5], v[130:131], 0, s[66:67]
	global_load_dwordx2 v[8:9], v[4:5], off sc1
	v_lshl_add_u32 v12, s17, 7, v217
	v_lshl_add_u32 v12, s72, 8, v12
	v_lshl_or_b32 v12, vcc_lo, 4, v12
	v_lshl_or_b32 v14, s16, 8, v222
	v_ashrrev_i32_e32 v13, 31, v12
	v_ashrrev_i32_e32 v15, 31, v14
	v_lshlrev_b64 v[12:13], 11, v[12:13]
	v_lshl_add_u64 v[12:13], s[42:43], 0, v[12:13]
	v_lshl_add_u64 v[12:13], v[14:15], 1, v[12:13]
	global_load_dwordx4 v[22:25], v[12:13], off
	global_load_dwordx4 v[26:29], v[12:13], off offset:256
	s_waitcnt vmcnt(33)
	v_lshlrev_b32_e32 v200, 16, v154
	v_and_b32_e32 v201, 0xffff0000, v154
	v_lshlrev_b32_e32 v154, 16, v155
	v_and_b32_e32 v155, 0xffff0000, v155
	v_pk_add_f32 v[154:155], v[154:155], 0 op_sel_hi:[1,0]
	s_waitcnt vmcnt(32)
	v_lshlrev_b32_e32 v202, 16, v156
	v_and_b32_e32 v203, 0xffff0000, v156
	v_lshlrev_b32_e32 v156, 16, v157
	v_and_b32_e32 v157, 0xffff0000, v157
	s_waitcnt vmcnt(29)
	v_lshlrev_b32_e32 v208, 16, v162
	v_and_b32_e32 v209, 0xffff0000, v162
	v_lshlrev_b32_e32 v162, 16, v163
	v_and_b32_e32 v163, 0xffff0000, v163
	v_pk_add_f32 v[156:157], v[156:157], 0 op_sel_hi:[1,0]
	v_lshlrev_b32_e32 v204, 16, v158
	v_and_b32_e32 v205, 0xffff0000, v158
	v_lshlrev_b32_e32 v158, 16, v159
	v_and_b32_e32 v159, 0xffff0000, v159
	v_pk_add_f32 v[154:155], v[154:155], v[162:163]
	s_waitcnt vmcnt(28)
	v_lshlrev_b32_e32 v162, 16, v164
	v_and_b32_e32 v163, 0xffff0000, v164
	v_lshlrev_b32_e32 v164, 16, v165
	v_and_b32_e32 v165, 0xffff0000, v165
	v_pk_add_f32 v[158:159], v[158:159], 0 op_sel_hi:[1,0]
	v_lshlrev_b32_e32 v206, 16, v160
	v_and_b32_e32 v207, 0xffff0000, v160
	v_lshlrev_b32_e32 v160, 16, v161
	v_and_b32_e32 v161, 0xffff0000, v161
	v_pk_add_f32 v[156:157], v[156:157], v[164:165]
	s_waitcnt vmcnt(27)
	v_lshlrev_b32_e32 v164, 16, v166
	v_and_b32_e32 v165, 0xffff0000, v166
	v_lshlrev_b32_e32 v166, 16, v167
	v_and_b32_e32 v167, 0xffff0000, v167
	v_pk_add_f32 v[160:161], v[160:161], 0 op_sel_hi:[1,0]
	v_pk_add_f32 v[158:159], v[158:159], v[166:167]
	s_waitcnt vmcnt(26)
	v_lshlrev_b32_e32 v166, 16, v168
	v_and_b32_e32 v167, 0xffff0000, v168
	v_lshlrev_b32_e32 v168, 16, v169
	v_and_b32_e32 v169, 0xffff0000, v169
	v_pk_add_f32 v[160:161], v[160:161], v[168:169]
	s_waitcnt vmcnt(25)
	v_lshlrev_b32_e32 v168, 16, v170
	v_and_b32_e32 v169, 0xffff0000, v170
	v_lshlrev_b32_e32 v170, 16, v171
	v_and_b32_e32 v171, 0xffff0000, v171
	v_pk_add_f32 v[154:155], v[154:155], v[170:171]
	s_waitcnt vmcnt(24)
	v_lshlrev_b32_e32 v170, 16, v172
	v_and_b32_e32 v171, 0xffff0000, v172
	v_lshlrev_b32_e32 v172, 16, v173
	v_and_b32_e32 v173, 0xffff0000, v173
	v_pk_add_f32 v[156:157], v[156:157], v[172:173]
	s_waitcnt vmcnt(23)
	v_lshlrev_b32_e32 v172, 16, v175
	v_and_b32_e32 v173, 0xffff0000, v175
	v_pk_add_f32 v[202:203], v[202:203], 0 op_sel_hi:[1,0]
	v_pk_add_f32 v[158:159], v[158:159], v[172:173]
	s_waitcnt vmcnt(22)
	v_lshlrev_b32_e32 v172, 16, v177
	v_and_b32_e32 v173, 0xffff0000, v177
	v_pk_add_f32 v[204:205], v[204:205], 0 op_sel_hi:[1,0]
	v_pk_add_f32 v[162:163], v[202:203], v[162:163]
	v_pk_add_f32 v[160:161], v[160:161], v[172:173]
	s_waitcnt vmcnt(21)
	v_lshlrev_b32_e32 v172, 16, v179
	v_and_b32_e32 v173, 0xffff0000, v179
	v_pk_add_f32 v[200:201], v[200:201], 0 op_sel_hi:[1,0]
	v_pk_add_f32 v[206:207], v[206:207], 0 op_sel_hi:[1,0]
	v_pk_add_f32 v[164:165], v[204:205], v[164:165]
	v_pk_add_f32 v[162:163], v[162:163], v[170:171]
	v_lshlrev_b32_e32 v170, 16, v174
	v_and_b32_e32 v171, 0xffff0000, v174
	v_pk_add_f32 v[154:155], v[154:155], v[172:173]
	s_waitcnt vmcnt(20)
	v_lshlrev_b32_e32 v172, 16, v181
	v_and_b32_e32 v173, 0xffff0000, v181
	v_pk_add_f32 v[200:201], v[200:201], v[208:209]
	v_pk_add_f32 v[166:167], v[206:207], v[166:167]
	v_pk_add_f32 v[164:165], v[164:165], v[170:171]
	v_lshlrev_b32_e32 v170, 16, v176
	v_and_b32_e32 v171, 0xffff0000, v176
	v_pk_add_f32 v[156:157], v[156:157], v[172:173]
	s_waitcnt vmcnt(19)
	v_lshlrev_b32_e32 v172, 16, v183
	v_and_b32_e32 v173, 0xffff0000, v183
	v_pk_add_f32 v[168:169], v[200:201], v[168:169]
	v_pk_add_f32 v[166:167], v[166:167], v[170:171]
	v_lshlrev_b32_e32 v170, 16, v178
	v_and_b32_e32 v171, 0xffff0000, v178
	v_pk_add_f32 v[158:159], v[158:159], v[172:173]
	s_waitcnt vmcnt(18)
	v_lshlrev_b32_e32 v172, 16, v185
	v_and_b32_e32 v173, 0xffff0000, v185
	v_pk_add_f32 v[168:169], v[168:169], v[170:171]
	v_lshlrev_b32_e32 v170, 16, v180
	v_and_b32_e32 v171, 0xffff0000, v180
	v_pk_add_f32 v[160:161], v[160:161], v[172:173]
	s_waitcnt vmcnt(17)
	v_lshlrev_b32_e32 v172, 16, v187
	v_and_b32_e32 v173, 0xffff0000, v187
	v_pk_add_f32 v[162:163], v[162:163], v[170:171]
	v_lshlrev_b32_e32 v170, 16, v182
	v_and_b32_e32 v171, 0xffff0000, v182
	v_pk_add_f32 v[172:173], v[154:155], v[172:173]
	s_waitcnt vmcnt(16)
	v_lshlrev_b32_e32 v154, 16, v188
	v_and_b32_e32 v155, 0xffff0000, v188
	v_pk_add_f32 v[164:165], v[164:165], v[170:171]
	v_pk_add_f32 v[174:175], v[162:163], v[154:155]
	s_waitcnt vmcnt(15)
	v_lshlrev_b32_e32 v154, 16, v190
	v_and_b32_e32 v155, 0xffff0000, v190
	v_pk_add_f32 v[164:165], v[164:165], v[154:155]
	s_waitcnt vmcnt(14)
	v_lshlrev_b32_e32 v154, 16, v193
	v_and_b32_e32 v155, 0xffff0000, v193
	s_lshl_b32 s33, s72, 8
	v_lshl_add_u32 v162, s17, 7, v217
	v_pk_add_f32 v[160:161], v[160:161], v[154:155]
	s_lshl_b32 s36, vcc_lo, 4
	v_add_u32_e32 v154, s33, v162
	v_or_b32_e32 v154, s36, v154
	v_lshlrev_b32_e32 v170, 16, v184
	v_and_b32_e32 v171, 0xffff0000, v184
	v_ashrrev_i32_e32 v155, 31, v154
	v_pk_add_f32 v[166:167], v[166:167], v[170:171]
	v_lshlrev_b32_e32 v170, 16, v186
	v_and_b32_e32 v171, 0xffff0000, v186
	v_lshl_or_b32 v200, s16, 8, v222
	v_lshlrev_b64 v[154:155], 11, v[154:155]
	v_pk_add_f32 v[168:169], v[168:169], v[170:171]
	v_lshlrev_b32_e32 v170, 16, v189
	v_and_b32_e32 v171, 0xffff0000, v189
	v_ashrrev_i32_e32 v201, 31, v200
	v_lshl_add_u64 v[154:155], s[42:43], 0, v[154:155]
	v_pk_add_f32 v[170:171], v[156:157], v[170:171]
	v_lshlrev_b32_e32 v156, 16, v191
	v_and_b32_e32 v157, 0xffff0000, v191
	v_lshl_add_u64 v[178:179], v[200:201], 1, v[154:155]
	v_pk_add_f32 v[158:159], v[158:159], v[156:157]
	v_lshlrev_b32_e32 v176, 16, v192
	v_and_b32_e32 v177, 0xffff0000, v192
	v_pk_add_f32 v[176:177], v[166:167], v[176:177]
	s_waitcnt vmcnt(13)
	v_lshlrev_b32_e32 v166, 16, v152
	v_and_b32_e32 v167, 0xffff0000, v152
	v_lshlrev_b32_e32 v152, 16, v153
	v_and_b32_e32 v153, 0xffff0000, v153
	v_pk_add_f32 v[168:169], v[168:169], v[166:167]
	s_waitcnt vmcnt(12)
	v_lshlrev_b32_e32 v166, 16, v150
	v_and_b32_e32 v167, 0xffff0000, v150
	v_pk_add_f32 v[152:153], v[172:173], v[152:153]
	v_lshlrev_b32_e32 v150, 16, v151
	v_and_b32_e32 v151, 0xffff0000, v151
	v_pk_add_f32 v[172:173], v[174:175], v[166:167]
	s_waitcnt vmcnt(11)
	v_lshlrev_b32_e32 v166, 16, v148
	v_and_b32_e32 v167, 0xffff0000, v148
	v_pk_add_f32 v[150:151], v[170:171], v[150:151]
	v_pk_add_f32 v[170:171], v[164:165], v[166:167]
	v_lshlrev_b32_e32 v148, 16, v149
	v_and_b32_e32 v149, 0xffff0000, v149
	v_pk_add_f32 v[148:149], v[158:159], v[148:149]
	s_waitcnt vmcnt(10)
	v_lshlrev_b32_e32 v158, 16, v144
	v_and_b32_e32 v159, 0xffff0000, v144
	v_lshlrev_b32_e32 v144, 16, v145
	v_and_b32_e32 v145, 0xffff0000, v145
	v_pk_add_f32 v[144:145], v[160:161], v[144:145]
	s_waitcnt vmcnt(9)
	v_lshlrev_b32_e32 v160, 16, v146
	v_and_b32_e32 v161, 0xffff0000, v146
	v_lshlrev_b32_e32 v146, 16, v147
	v_and_b32_e32 v147, 0xffff0000, v147
	v_pk_add_f32 v[146:147], v[152:153], v[146:147]
	v_pk_add_f32 v[152:153], v[168:169], v[160:161]
	s_waitcnt vmcnt(8)
	v_lshlrev_b32_e32 v160, 16, v142
	v_and_b32_e32 v161, 0xffff0000, v142
	v_lshlrev_b32_e32 v142, 16, v143
	v_and_b32_e32 v143, 0xffff0000, v143
	v_pk_add_f32 v[142:143], v[150:151], v[142:143]
	v_pk_add_f32 v[150:151], v[172:173], v[160:161]
	s_waitcnt vmcnt(7)
	v_lshlrev_b32_e32 v160, 16, v140
	v_and_b32_e32 v161, 0xffff0000, v140
	v_lshlrev_b32_e32 v140, 16, v141
	v_and_b32_e32 v141, 0xffff0000, v141
	v_pk_add_f32 v[158:159], v[176:177], v[158:159]
	v_pk_add_f32 v[148:149], v[148:149], v[140:141]
	s_waitcnt vmcnt(6)
	v_lshlrev_b32_e32 v140, 16, v136
	v_and_b32_e32 v141, 0xffff0000, v136
	v_pk_add_f32 v[168:169], v[170:171], v[160:161]
	v_pk_add_f32 v[170:171], v[158:159], v[140:141]
	s_waitcnt vmcnt(5)
	v_lshlrev_b32_e32 v140, 16, v138
	v_and_b32_e32 v141, 0xffff0000, v138
	v_lshlrev_b32_e32 v138, 16, v139
	v_and_b32_e32 v139, 0xffff0000, v139
	v_readlane_b32 s60, v254, 0
	v_pk_add_f32 v[146:147], v[146:147], v[138:139]
	s_waitcnt vmcnt(4)
	v_lshlrev_b32_e32 v138, 16, v134
	v_and_b32_e32 v139, 0xffff0000, v134
	v_lshlrev_b32_e32 v134, 16, v135
	v_and_b32_e32 v135, 0xffff0000, v135
	v_readlane_b32 s66, v254, 6
	v_readlane_b32 s67, v254, 7
	v_lshlrev_b32_e32 v136, 16, v137
	v_and_b32_e32 v137, 0xffff0000, v137
	v_pk_add_f32 v[134:135], v[142:143], v[134:135]
	v_lshl_add_u64 v[142:143], v[200:201], 2, s[66:67]
	v_pk_add_f32 v[136:137], v[144:145], v[136:137]
	v_pk_add_f32 v[172:173], v[152:153], v[140:141]
	v_pk_add_f32 v[174:175], v[150:151], v[138:139]
	global_load_dwordx4 v[150:153], v[142:143], off offset:16
	global_load_dwordx4 v[158:161], v[142:143], off
	global_load_dwordx4 v[138:141], v[142:143], off offset:528
	s_nop 0
	global_load_dwordx4 v[142:145], v[142:143], off offset:512
	s_waitcnt vmcnt(7)
	v_mov_b32_e32 v132, v6
	v_mov_b32_e32 v133, v7
	v_lshlrev_b32_e32 v176, 16, v132
	v_and_b32_e32 v177, 0xffff0000, v132
	v_lshlrev_b32_e32 v132, 16, v133
	v_and_b32_e32 v133, 0xffff0000, v133
	v_pk_add_f32 v[148:149], v[148:149], v[132:133]
	s_waitcnt vmcnt(6)
	v_mov_b32_e32 v130, v8
	v_mov_b32_e32 v131, v9
	v_lshlrev_b32_e32 v132, 16, v130
	v_and_b32_e32 v133, 0xffff0000, v130
	v_lshlrev_b32_e32 v130, 16, v131
	v_and_b32_e32 v131, 0xffff0000, v131
	v_pk_add_f32 v[168:169], v[168:169], v[176:177]
	v_pk_add_f32 v[170:171], v[170:171], v[132:133]
	v_pk_add_f32 v[176:177], v[136:137], v[130:131]
	s_waitcnt vmcnt(5)
	v_mov_b32_e32 v154, v22
	v_mov_b32_e32 v155, v23
	v_mov_b32_e32 v156, v24
	v_mov_b32_e32 v157, v25
	v_lshlrev_b32_e32 v130, 16, v154
	v_and_b32_e32 v131, 0xffff0000, v154
	v_lshlrev_b32_e32 v132, 16, v155
	v_and_b32_e32 v133, 0xffff0000, v155
	v_pk_fma_f32 v[132:133], v[146:147], 0.5, v[132:133] op_sel_hi:[1,0,1]
	v_pk_fma_f32 v[130:131], v[172:173], 0.5, v[130:131] op_sel_hi:[1,0,1]
	v_mul_f32_e32 v137, v133, v133
	v_mul_f32_e32 v136, v131, v131
	v_fmac_f32_e32 v136, v130, v130
	v_fmac_f32_e32 v137, v132, v132
	v_add_f32_e32 v154, v136, v137
	v_lshlrev_b32_e32 v146, 16, v156
	v_and_b32_e32 v147, 0xffff0000, v156
	v_lshlrev_b32_e32 v136, 16, v157
	v_and_b32_e32 v137, 0xffff0000, v157
	v_pk_fma_f32 v[136:137], v[134:135], 0.5, v[136:137] op_sel_hi:[1,0,1]
	v_pk_fma_f32 v[134:135], v[174:175], 0.5, v[146:147] op_sel_hi:[1,0,1]
	v_mul_f32_e32 v147, v137, v137
	v_mul_f32_e32 v146, v135, v135
	v_fmac_f32_e32 v146, v134, v134
	v_fmac_f32_e32 v147, v136, v136
	v_add_f32_e32 v146, v146, v147
	v_add_f32_e32 v156, v154, v146
	s_waitcnt vmcnt(4)
	v_mov_b32_e32 v164, v26
	v_mov_b32_e32 v165, v27
	v_mov_b32_e32 v166, v28
	v_mov_b32_e32 v167, v29
	v_lshlrev_b32_e32 v146, 16, v164
	v_and_b32_e32 v147, 0xffff0000, v164
	v_lshlrev_b32_e32 v154, 16, v165
	v_and_b32_e32 v155, 0xffff0000, v165
	v_pk_fma_f32 v[148:149], v[148:149], 0.5, v[154:155] op_sel_hi:[1,0,1]
	v_pk_fma_f32 v[146:147], v[168:169], 0.5, v[146:147] op_sel_hi:[1,0,1]
	v_mul_f32_e32 v155, v149, v149
	v_mul_f32_e32 v154, v147, v147
	v_fmac_f32_e32 v154, v146, v146
	v_fmac_f32_e32 v155, v148, v148
	v_add_f32_e32 v154, v154, v155
	v_add_f32_e32 v163, v156, v154
	v_lshlrev_b32_e32 v154, 16, v166
	v_and_b32_e32 v155, 0xffff0000, v166
	v_lshlrev_b32_e32 v156, 16, v167
	v_and_b32_e32 v157, 0xffff0000, v167
	v_pk_fma_f32 v[156:157], v[176:177], 0.5, v[156:157] op_sel_hi:[1,0,1]
	v_pk_fma_f32 v[154:155], v[170:171], 0.5, v[154:155] op_sel_hi:[1,0,1]
	v_mul_f32_e32 v165, v157, v157
	v_mul_f32_e32 v164, v155, v155
	v_fmac_f32_e32 v164, v154, v154
	v_fmac_f32_e32 v165, v156, v156
	v_add_f32_e32 v164, v164, v165
	v_and_b32_e32 v165, 64, v227
	v_add_f32_e32 v163, v163, v164
	v_xor_b32_e32 v164, 16, v227
	v_add_u32_e32 v165, 64, v165
	v_cmp_lt_i32_e32 vcc, v164, v165
	v_readlane_b32 s61, v254, 1
	v_readlane_b32 s62, v254, 2
	v_cndmask_b32_e32 v164, v227, v164, vcc
	v_lshlrev_b32_e32 v164, 2, v164
	v_mov_b32_e32 v164, v163
	s_nop 1
	v_permlane16_swap_b32_e32 v163, v164
	v_readlane_b32 s63, v254, 3
	v_readlane_b32 s64, v254, 4
	v_readlane_b32 s65, v254, 5
	s_waitcnt lgkmcnt(0)
	v_add_f32_e32 v163, v163, v164
	v_xor_b32_e32 v164, 32, v227
	v_cmp_lt_i32_e32 vcc, v164, v165
	s_nop 1
	v_cndmask_b32_e32 v164, v227, v164, vcc
	v_lshlrev_b32_e32 v164, 2, v164
	v_mov_b32_e32 v165, v163
	s_nop 1
	v_permlane32_swap_b32_e32 v163, v165
	v_or_b32_e32 v164, s36, v162
	s_and_saveexec_b64 s[58:59], s[10:11]
	s_cbranch_execz .LBB0_2147
	v_or_b32_e32 v162, s36, v162
	v_lshl_add_u32 v162, v162, 4, s93
	s_waitcnt lgkmcnt(0)
	v_add_f32_e32 v163, v163, v165
	ds_write_b32 v162, v163
